# stack: prompt-loop micro-trims + work-index prefetch + sample-unit K-fragment ring/lazy rescale
# baseline (speedup 1.0000x reference)
.Lst_noat2_0:
	s_or_b64 exec, exec, s[66:67]
.Lst_noat_0:
.Lst_bar2_0:
	s_waitcnt lgkmcnt(0)
	s_barrier
	s_add_i32 s93, s69, 1
	s_cmp_ge_u32 s93, s47
	s_cbranch_scc1 .Lst_exit
	s_cmp_gt_i32 s93, s50
	s_cbranch_scc1 .Lst_nosm1
	ds_read_b128 v[220:223], v194 offset:21504
	ds_read_b128 v[224:227], v194 offset:21536
	ds_read_b128 v[228:231], v194 offset:21568
	ds_read_b128 v[232:235], v194 offset:21600
	ds_read_b128 v[126:129], v194 offset:21760
	ds_read_b128 v[130:133], v194 offset:21792
	ds_read_b128 v[134:137], v194 offset:32256
	ds_read_b128 v[212:215], v194 offset:32288
	ds_read_b128 v[154:157], v194 offset:32320
	ds_read_b128 v[158:161], v194 offset:32352
	ds_read_b128 v[204:207], v194 offset:32512
	ds_read_b128 v[186:189], v194 offset:32544
	s_waitcnt lgkmcnt(11)
	v_mfma_f32_32x32x16_bf16 v[48:63], v[220:223], v[64:67], v[236:251]
	s_waitcnt lgkmcnt(10)
	v_mfma_f32_32x32x16_bf16 v[48:63], v[224:227], v[68:71], v[48:63]
	s_waitcnt lgkmcnt(9)
	v_mfma_f32_32x32x16_bf16 v[48:63], v[228:231], v[72:75], v[48:63]
	s_waitcnt lgkmcnt(8)
	v_mfma_f32_32x32x16_bf16 v[48:63], v[232:235], v[76:79], v[48:63]
	s_waitcnt lgkmcnt(7)
	v_mfma_f32_32x32x16_bf16 v[48:63], v[126:129], v[80:83], v[48:63]
	s_waitcnt lgkmcnt(6)
	v_mfma_f32_32x32x16_bf16 v[48:63], v[130:133], v[84:87], v[48:63]
	s_waitcnt lgkmcnt(5)
	v_mfma_f32_32x32x16_bf16 v[32:47], v[134:137], v[64:67], v[236:251]
	s_waitcnt lgkmcnt(4)
	v_mfma_f32_32x32x16_bf16 v[32:47], v[212:215], v[68:71], v[32:47]
	s_waitcnt lgkmcnt(3)
	v_mfma_f32_32x32x16_bf16 v[32:47], v[154:157], v[72:75], v[32:47]
	s_waitcnt lgkmcnt(2)
	v_mfma_f32_32x32x16_bf16 v[32:47], v[158:161], v[76:79], v[32:47]
	s_waitcnt lgkmcnt(1)
	v_mfma_f32_32x32x16_bf16 v[32:47], v[204:207], v[80:83], v[32:47]
	s_waitcnt lgkmcnt(0)
	v_mfma_f32_32x32x16_bf16 v[32:47], v[186:189], v[84:87], v[32:47]
	v_max3_f32 v153, v48, v49, v50
	v_max3_f32 v153, v153, v51, v52
	v_max3_f32 v153, v153, v53, v54
	v_max3_f32 v153, v153, v55, v56
	v_max3_f32 v153, v153, v57, v58
	v_max3_f32 v153, v153, v59, v60
	v_max3_f32 v153, v153, v61, v62
	v_max_f32_e32 v153, v153, v63
	s_nop 3
	v_max3_f32 v153, v153, v32, v33
	v_max3_f32 v153, v153, v34, v35
	v_max3_f32 v153, v153, v36, v37
	v_max3_f32 v153, v153, v38, v39
	v_max3_f32 v153, v153, v40, v41
	v_max3_f32 v153, v153, v42, v43
	v_max3_f32 v153, v153, v44, v45
	v_max3_f32 v153, v153, v46, v47
	v_cmp_lt_f32_e32 vcc, 0x41000000, v153
	s_cbranch_vccz .Lst_norescale_1
	v_mov_b32_e32 v154, v153
	s_nop 1
	v_permlane32_swap_b32_e32 v153, v154
	v_max_f32_e32 v153, v153, v154
	v_max_f32_e32 v154, 0, v153
	v_exp_f32_e64 v152, -v154
	v_sub_f32_e32 v236, v236, v154
	v_sub_f32_e32 v237, v237, v154
	v_sub_f32_e32 v238, v238, v154
	v_sub_f32_e32 v239, v239, v154
	v_sub_f32_e32 v240, v240, v154
	v_sub_f32_e32 v241, v241, v154
	v_sub_f32_e32 v242, v242, v154
	v_sub_f32_e32 v243, v243, v154
	v_sub_f32_e32 v244, v244, v154
	v_sub_f32_e32 v245, v245, v154
	v_sub_f32_e32 v246, v246, v154
	v_sub_f32_e32 v247, v247, v154
	v_sub_f32_e32 v248, v248, v154
	v_sub_f32_e32 v249, v249, v154
	v_sub_f32_e32 v250, v250, v154
	v_sub_f32_e32 v251, v251, v154
	v_pk_mul_f32 v[30:31], v[30:31], v[152:153] op_sel_hi:[1,0]
	v_pk_mul_f32 v[28:29], v[28:29], v[152:153] op_sel_hi:[1,0]
	v_pk_mul_f32 v[26:27], v[26:27], v[152:153] op_sel_hi:[1,0]
	v_pk_mul_f32 v[24:25], v[24:25], v[152:153] op_sel_hi:[1,0]
	v_pk_mul_f32 v[22:23], v[22:23], v[152:153] op_sel_hi:[1,0]
	v_pk_mul_f32 v[20:21], v[20:21], v[152:153] op_sel_hi:[1,0]
	v_pk_mul_f32 v[18:19], v[18:19], v[152:153] op_sel_hi:[1,0]
	v_pk_mul_f32 v[16:17], v[16:17], v[152:153] op_sel_hi:[1,0]
	v_pk_mul_f32 v[14:15], v[14:15], v[152:153] op_sel_hi:[1,0]
	v_pk_mul_f32 v[12:13], v[12:13], v[152:153] op_sel_hi:[1,0]
	v_pk_mul_f32 v[10:11], v[10:11], v[152:153] op_sel_hi:[1,0]
	v_pk_mul_f32 v[8:9], v[8:9], v[152:153] op_sel_hi:[1,0]
	v_pk_mul_f32 v[6:7], v[6:7], v[152:153] op_sel_hi:[1,0]
	v_pk_mul_f32 v[4:5], v[4:5], v[152:153] op_sel_hi:[1,0]
	v_pk_mul_f32 v[2:3], v[2:3], v[152:153] op_sel_hi:[1,0]
	v_pk_mul_f32 v[0:1], v[0:1], v[152:153] op_sel_hi:[1,0]
	v_mul_f32_e32 v151, v151, v152

.Lst_noat2_1:
	s_or_b64 exec, exec, s[66:67]
.Lst_noat_1:
.Lst_bar2_1:
	s_waitcnt lgkmcnt(0)
	s_barrier
	s_add_i32 s93, s69, 2
	s_cmp_ge_u32 s93, s47
	s_cbranch_scc1 .Lst_exit
	s_cmp_gt_i32 s93, s50
	s_cbranch_scc1 .Lst_nosm2
	ds_read_b128 v[220:223], v194
	ds_read_b128 v[224:227], v194 offset:32
	ds_read_b128 v[228:231], v194 offset:64
	ds_read_b128 v[232:235], v194 offset:96
	ds_read_b128 v[126:129], v194 offset:256
	ds_read_b128 v[130:133], v194 offset:288
	ds_read_b128 v[134:137], v194 offset:10752
	ds_read_b128 v[212:215], v194 offset:10784
	ds_read_b128 v[154:157], v194 offset:10816
	ds_read_b128 v[158:161], v194 offset:10848
	ds_read_b128 v[204:207], v194 offset:11008
	ds_read_b128 v[186:189], v194 offset:11040
	s_waitcnt lgkmcnt(11)
	v_mfma_f32_32x32x16_bf16 v[48:63], v[220:223], v[64:67], v[236:251]
	s_waitcnt lgkmcnt(10)
	v_mfma_f32_32x32x16_bf16 v[48:63], v[224:227], v[68:71], v[48:63]
	s_waitcnt lgkmcnt(9)
	v_mfma_f32_32x32x16_bf16 v[48:63], v[228:231], v[72:75], v[48:63]
	s_waitcnt lgkmcnt(8)
	v_mfma_f32_32x32x16_bf16 v[48:63], v[232:235], v[76:79], v[48:63]
	s_waitcnt lgkmcnt(7)
	v_mfma_f32_32x32x16_bf16 v[48:63], v[126:129], v[80:83], v[48:63]
	s_waitcnt lgkmcnt(6)
	v_mfma_f32_32x32x16_bf16 v[48:63], v[130:133], v[84:87], v[48:63]
	s_waitcnt lgkmcnt(5)
	v_mfma_f32_32x32x16_bf16 v[32:47], v[134:137], v[64:67], v[236:251]
	s_waitcnt lgkmcnt(4)
	v_mfma_f32_32x32x16_bf16 v[32:47], v[212:215], v[68:71], v[32:47]
	s_waitcnt lgkmcnt(3)
	v_mfma_f32_32x32x16_bf16 v[32:47], v[154:157], v[72:75], v[32:47]
	s_waitcnt lgkmcnt(2)
	v_mfma_f32_32x32x16_bf16 v[32:47], v[158:161], v[76:79], v[32:47]
	s_waitcnt lgkmcnt(1)
	v_mfma_f32_32x32x16_bf16 v[32:47], v[204:207], v[80:83], v[32:47]
	s_waitcnt lgkmcnt(0)
	v_mfma_f32_32x32x16_bf16 v[32:47], v[186:189], v[84:87], v[32:47]
	v_max3_f32 v153, v48, v49, v50
	v_max3_f32 v153, v153, v51, v52
	v_max3_f32 v153, v153, v53, v54
	v_max3_f32 v153, v153, v55, v56
	v_max3_f32 v153, v153, v57, v58
	v_max3_f32 v153, v153, v59, v60
	v_max3_f32 v153, v153, v61, v62
	v_max_f32_e32 v153, v153, v63
	s_nop 3
	v_max3_f32 v153, v153, v32, v33
	v_max3_f32 v153, v153, v34, v35
	v_max3_f32 v153, v153, v36, v37
	v_max3_f32 v153, v153, v38, v39
	v_max3_f32 v153, v153, v40, v41
	v_max3_f32 v153, v153, v42, v43
	v_max3_f32 v153, v153, v44, v45
	v_max3_f32 v153, v153, v46, v47
	v_cmp_lt_f32_e32 vcc, 0x41000000, v153
	s_cbranch_vccz .Lst_norescale_2
	v_mov_b32_e32 v154, v153
	s_nop 1
	v_permlane32_swap_b32_e32 v153, v154
	v_max_f32_e32 v153, v153, v154
	v_max_f32_e32 v154, 0, v153
	v_exp_f32_e64 v152, -v154
	v_sub_f32_e32 v236, v236, v154
	v_sub_f32_e32 v237, v237, v154
	v_sub_f32_e32 v238, v238, v154
	v_sub_f32_e32 v239, v239, v154
	v_sub_f32_e32 v240, v240, v154
	v_sub_f32_e32 v241, v241, v154
	v_sub_f32_e32 v242, v242, v154
	v_sub_f32_e32 v243, v243, v154
	v_sub_f32_e32 v244, v244, v154
	v_sub_f32_e32 v245, v245, v154
	v_sub_f32_e32 v246, v246, v154
	v_sub_f32_e32 v247, v247, v154
	v_sub_f32_e32 v248, v248, v154
	v_sub_f32_e32 v249, v249, v154
	v_sub_f32_e32 v250, v250, v154
	v_sub_f32_e32 v251, v251, v154
	v_pk_mul_f32 v[30:31], v[30:31], v[152:153] op_sel_hi:[1,0]
	v_pk_mul_f32 v[28:29], v[28:29], v[152:153] op_sel_hi:[1,0]
	v_pk_mul_f32 v[26:27], v[26:27], v[152:153] op_sel_hi:[1,0]
	v_pk_mul_f32 v[24:25], v[24:25], v[152:153] op_sel_hi:[1,0]
	v_pk_mul_f32 v[22:23], v[22:23], v[152:153] op_sel_hi:[1,0]
	v_pk_mul_f32 v[20:21], v[20:21], v[152:153] op_sel_hi:[1,0]
	v_pk_mul_f32 v[18:19], v[18:19], v[152:153] op_sel_hi:[1,0]
	v_pk_mul_f32 v[16:17], v[16:17], v[152:153] op_sel_hi:[1,0]
	v_pk_mul_f32 v[14:15], v[14:15], v[152:153] op_sel_hi:[1,0]
	v_pk_mul_f32 v[12:13], v[12:13], v[152:153] op_sel_hi:[1,0]
	v_pk_mul_f32 v[10:11], v[10:11], v[152:153] op_sel_hi:[1,0]
	v_pk_mul_f32 v[8:9], v[8:9], v[152:153] op_sel_hi:[1,0]
	v_pk_mul_f32 v[6:7], v[6:7], v[152:153] op_sel_hi:[1,0]
	v_pk_mul_f32 v[4:5], v[4:5], v[152:153] op_sel_hi:[1,0]
	v_pk_mul_f32 v[2:3], v[2:3], v[152:153] op_sel_hi:[1,0]
	v_pk_mul_f32 v[0:1], v[0:1], v[152:153] op_sel_hi:[1,0]
	v_mul_f32_e32 v151, v151, v152

.Lst_noat2_2:
	s_or_b64 exec, exec, s[66:67]
.Lst_noat_2:
.Lst_bar2_2:
	s_waitcnt lgkmcnt(0)
	s_barrier
	s_add_i32 s93, s69, 3
	s_cmp_ge_u32 s93, s47
	s_cbranch_scc1 .Lst_exit
	s_cmp_gt_i32 s93, s50
	s_cbranch_scc1 .Lst_nosm3
	ds_read_b128 v[220:223], v194 offset:21504
	ds_read_b128 v[224:227], v194 offset:21536
	ds_read_b128 v[228:231], v194 offset:21568
	ds_read_b128 v[232:235], v194 offset:21600
	ds_read_b128 v[126:129], v194 offset:21760
	ds_read_b128 v[130:133], v194 offset:21792
	ds_read_b128 v[134:137], v194 offset:32256
	ds_read_b128 v[212:215], v194 offset:32288
	ds_read_b128 v[154:157], v194 offset:32320
	ds_read_b128 v[158:161], v194 offset:32352
	ds_read_b128 v[204:207], v194 offset:32512
	ds_read_b128 v[186:189], v194 offset:32544
	s_waitcnt lgkmcnt(11)
	v_mfma_f32_32x32x16_bf16 v[48:63], v[220:223], v[64:67], v[236:251]
	s_waitcnt lgkmcnt(10)
	v_mfma_f32_32x32x16_bf16 v[48:63], v[224:227], v[68:71], v[48:63]
	s_waitcnt lgkmcnt(9)
	v_mfma_f32_32x32x16_bf16 v[48:63], v[228:231], v[72:75], v[48:63]
	s_waitcnt lgkmcnt(8)
	v_mfma_f32_32x32x16_bf16 v[48:63], v[232:235], v[76:79], v[48:63]
	s_waitcnt lgkmcnt(7)
	v_mfma_f32_32x32x16_bf16 v[48:63], v[126:129], v[80:83], v[48:63]
	s_waitcnt lgkmcnt(6)
	v_mfma_f32_32x32x16_bf16 v[48:63], v[130:133], v[84:87], v[48:63]
	s_waitcnt lgkmcnt(5)
	v_mfma_f32_32x32x16_bf16 v[32:47], v[134:137], v[64:67], v[236:251]
	s_waitcnt lgkmcnt(4)
	v_mfma_f32_32x32x16_bf16 v[32:47], v[212:215], v[68:71], v[32:47]
	s_waitcnt lgkmcnt(3)
	v_mfma_f32_32x32x16_bf16 v[32:47], v[154:157], v[72:75], v[32:47]
	s_waitcnt lgkmcnt(2)
	v_mfma_f32_32x32x16_bf16 v[32:47], v[158:161], v[76:79], v[32:47]
	s_waitcnt lgkmcnt(1)
	v_mfma_f32_32x32x16_bf16 v[32:47], v[204:207], v[80:83], v[32:47]
	s_waitcnt lgkmcnt(0)
	v_mfma_f32_32x32x16_bf16 v[32:47], v[186:189], v[84:87], v[32:47]
	v_max3_f32 v153, v48, v49, v50
	v_max3_f32 v153, v153, v51, v52
	v_max3_f32 v153, v153, v53, v54
	v_max3_f32 v153, v153, v55, v56
	v_max3_f32 v153, v153, v57, v58
	v_max3_f32 v153, v153, v59, v60
	v_max3_f32 v153, v153, v61, v62
	v_max_f32_e32 v153, v153, v63
	s_nop 3
	v_max3_f32 v153, v153, v32, v33
	v_max3_f32 v153, v153, v34, v35
	v_max3_f32 v153, v153, v36, v37
	v_max3_f32 v153, v153, v38, v39
	v_max3_f32 v153, v153, v40, v41
	v_max3_f32 v153, v153, v42, v43
	v_max3_f32 v153, v153, v44, v45
	v_max3_f32 v153, v153, v46, v47
	v_cmp_lt_f32_e32 vcc, 0x41000000, v153
	s_cbranch_vccz .Lst_norescale_3
	v_mov_b32_e32 v154, v153
	s_nop 1
	v_permlane32_swap_b32_e32 v153, v154
	v_max_f32_e32 v153, v153, v154
	v_max_f32_e32 v154, 0, v153
	v_exp_f32_e64 v152, -v154
	v_sub_f32_e32 v236, v236, v154
	v_sub_f32_e32 v237, v237, v154
	v_sub_f32_e32 v238, v238, v154
	v_sub_f32_e32 v239, v239, v154
	v_sub_f32_e32 v240, v240, v154
	v_sub_f32_e32 v241, v241, v154
	v_sub_f32_e32 v242, v242, v154
	v_sub_f32_e32 v243, v243, v154
	v_sub_f32_e32 v244, v244, v154
	v_sub_f32_e32 v245, v245, v154
	v_sub_f32_e32 v246, v246, v154
	v_sub_f32_e32 v247, v247, v154
	v_sub_f32_e32 v248, v248, v154
	v_sub_f32_e32 v249, v249, v154
	v_sub_f32_e32 v250, v250, v154
	v_sub_f32_e32 v251, v251, v154
	v_pk_mul_f32 v[30:31], v[30:31], v[152:153] op_sel_hi:[1,0]
	v_pk_mul_f32 v[28:29], v[28:29], v[152:153] op_sel_hi:[1,0]
	v_pk_mul_f32 v[26:27], v[26:27], v[152:153] op_sel_hi:[1,0]
	v_pk_mul_f32 v[24:25], v[24:25], v[152:153] op_sel_hi:[1,0]
	v_pk_mul_f32 v[22:23], v[22:23], v[152:153] op_sel_hi:[1,0]
	v_pk_mul_f32 v[20:21], v[20:21], v[152:153] op_sel_hi:[1,0]
	v_pk_mul_f32 v[18:19], v[18:19], v[152:153] op_sel_hi:[1,0]
	v_pk_mul_f32 v[16:17], v[16:17], v[152:153] op_sel_hi:[1,0]
	v_pk_mul_f32 v[14:15], v[14:15], v[152:153] op_sel_hi:[1,0]
	v_pk_mul_f32 v[12:13], v[12:13], v[152:153] op_sel_hi:[1,0]
	v_pk_mul_f32 v[10:11], v[10:11], v[152:153] op_sel_hi:[1,0]
	v_pk_mul_f32 v[8:9], v[8:9], v[152:153] op_sel_hi:[1,0]
	v_pk_mul_f32 v[6:7], v[6:7], v[152:153] op_sel_hi:[1,0]
	v_pk_mul_f32 v[4:5], v[4:5], v[152:153] op_sel_hi:[1,0]
	v_pk_mul_f32 v[2:3], v[2:3], v[152:153] op_sel_hi:[1,0]
	v_pk_mul_f32 v[0:1], v[0:1], v[152:153] op_sel_hi:[1,0]
	v_mul_f32_e32 v151, v151, v152

.Lst_noat2_3:
	s_or_b64 exec, exec, s[66:67]
.Lst_noat_3:
.Lst_bar2_3:
	s_waitcnt lgkmcnt(0)
	s_barrier
	s_add_i32 s93, s69, 4
	s_cmp_ge_u32 s93, s47
	s_cbranch_scc1 .Lst_exit
	s_cmp_gt_i32 s93, s50
	s_cbranch_scc1 .Lst_nosm4
	ds_read_b128 v[220:223], v194
	ds_read_b128 v[224:227], v194 offset:32
	ds_read_b128 v[228:231], v194 offset:64
	ds_read_b128 v[232:235], v194 offset:96
	ds_read_b128 v[126:129], v194 offset:256
	ds_read_b128 v[130:133], v194 offset:288
	ds_read_b128 v[134:137], v194 offset:10752
	ds_read_b128 v[212:215], v194 offset:10784
	ds_read_b128 v[154:157], v194 offset:10816
	ds_read_b128 v[158:161], v194 offset:10848
	ds_read_b128 v[204:207], v194 offset:11008
	ds_read_b128 v[186:189], v194 offset:11040
	s_waitcnt lgkmcnt(11)
	v_mfma_f32_32x32x16_bf16 v[48:63], v[220:223], v[64:67], v[236:251]
	s_waitcnt lgkmcnt(10)
	v_mfma_f32_32x32x16_bf16 v[48:63], v[224:227], v[68:71], v[48:63]
	s_waitcnt lgkmcnt(9)
	v_mfma_f32_32x32x16_bf16 v[48:63], v[228:231], v[72:75], v[48:63]
	s_waitcnt lgkmcnt(8)
	v_mfma_f32_32x32x16_bf16 v[48:63], v[232:235], v[76:79], v[48:63]
	s_waitcnt lgkmcnt(7)
	v_mfma_f32_32x32x16_bf16 v[48:63], v[126:129], v[80:83], v[48:63]
	s_waitcnt lgkmcnt(6)
	v_mfma_f32_32x32x16_bf16 v[48:63], v[130:133], v[84:87], v[48:63]
	s_waitcnt lgkmcnt(5)
	v_mfma_f32_32x32x16_bf16 v[32:47], v[134:137], v[64:67], v[236:251]
	s_waitcnt lgkmcnt(4)
	v_mfma_f32_32x32x16_bf16 v[32:47], v[212:215], v[68:71], v[32:47]
	s_waitcnt lgkmcnt(3)
	v_mfma_f32_32x32x16_bf16 v[32:47], v[154:157], v[72:75], v[32:47]
	s_waitcnt lgkmcnt(2)
	v_mfma_f32_32x32x16_bf16 v[32:47], v[158:161], v[76:79], v[32:47]
	s_waitcnt lgkmcnt(1)
	v_mfma_f32_32x32x16_bf16 v[32:47], v[204:207], v[80:83], v[32:47]
	s_waitcnt lgkmcnt(0)
	v_mfma_f32_32x32x16_bf16 v[32:47], v[186:189], v[84:87], v[32:47]
	v_max3_f32 v153, v48, v49, v50
	v_max3_f32 v153, v153, v51, v52
	v_max3_f32 v153, v153, v53, v54
	v_max3_f32 v153, v153, v55, v56
	v_max3_f32 v153, v153, v57, v58
	v_max3_f32 v153, v153, v59, v60
	v_max3_f32 v153, v153, v61, v62
	v_max_f32_e32 v153, v153, v63
	s_nop 3
	v_max3_f32 v153, v153, v32, v33
	v_max3_f32 v153, v153, v34, v35
	v_max3_f32 v153, v153, v36, v37
	v_max3_f32 v153, v153, v38, v39
	v_max3_f32 v153, v153, v40, v41
	v_max3_f32 v153, v153, v42, v43
	v_max3_f32 v153, v153, v44, v45
	v_max3_f32 v153, v153, v46, v47
	v_cmp_lt_f32_e32 vcc, 0x41000000, v153
	s_cbranch_vccz .Lst_norescale_4
	v_mov_b32_e32 v154, v153
	s_nop 1
	v_permlane32_swap_b32_e32 v153, v154
	v_max_f32_e32 v153, v153, v154
	v_max_f32_e32 v154, 0, v153
	v_exp_f32_e64 v152, -v154
	v_sub_f32_e32 v236, v236, v154
	v_sub_f32_e32 v237, v237, v154
	v_sub_f32_e32 v238, v238, v154
	v_sub_f32_e32 v239, v239, v154
	v_sub_f32_e32 v240, v240, v154
	v_sub_f32_e32 v241, v241, v154
	v_sub_f32_e32 v242, v242, v154
	v_sub_f32_e32 v243, v243, v154
	v_sub_f32_e32 v244, v244, v154
	v_sub_f32_e32 v245, v245, v154
	v_sub_f32_e32 v246, v246, v154
	v_sub_f32_e32 v247, v247, v154
	v_sub_f32_e32 v248, v248, v154
	v_sub_f32_e32 v249, v249, v154
	v_sub_f32_e32 v250, v250, v154
	v_sub_f32_e32 v251, v251, v154
	v_pk_mul_f32 v[30:31], v[30:31], v[152:153] op_sel_hi:[1,0]
	v_pk_mul_f32 v[28:29], v[28:29], v[152:153] op_sel_hi:[1,0]
	v_pk_mul_f32 v[26:27], v[26:27], v[152:153] op_sel_hi:[1,0]
	v_pk_mul_f32 v[24:25], v[24:25], v[152:153] op_sel_hi:[1,0]
	v_pk_mul_f32 v[22:23], v[22:23], v[152:153] op_sel_hi:[1,0]
	v_pk_mul_f32 v[20:21], v[20:21], v[152:153] op_sel_hi:[1,0]
	v_pk_mul_f32 v[18:19], v[18:19], v[152:153] op_sel_hi:[1,0]
	v_pk_mul_f32 v[16:17], v[16:17], v[152:153] op_sel_hi:[1,0]
	v_pk_mul_f32 v[14:15], v[14:15], v[152:153] op_sel_hi:[1,0]
	v_pk_mul_f32 v[12:13], v[12:13], v[152:153] op_sel_hi:[1,0]
	v_pk_mul_f32 v[10:11], v[10:11], v[152:153] op_sel_hi:[1,0]
	v_pk_mul_f32 v[8:9], v[8:9], v[152:153] op_sel_hi:[1,0]
	v_pk_mul_f32 v[6:7], v[6:7], v[152:153] op_sel_hi:[1,0]
	v_pk_mul_f32 v[4:5], v[4:5], v[152:153] op_sel_hi:[1,0]
	v_pk_mul_f32 v[2:3], v[2:3], v[152:153] op_sel_hi:[1,0]
	v_pk_mul_f32 v[0:1], v[0:1], v[152:153] op_sel_hi:[1,0]
	v_mul_f32_e32 v151, v151, v152

.Lst_noat2_4:
	s_or_b64 exec, exec, s[66:67]
.Lst_noat_4:
.Lst_bar2_4:
	s_waitcnt lgkmcnt(0)
	s_barrier
	s_add_i32 s93, s69, 5
	s_cmp_ge_u32 s93, s47
	s_cbranch_scc1 .Lst_exit
	s_cmp_gt_i32 s93, s50
	s_cbranch_scc1 .Lst_nosm5
	ds_read_b128 v[220:223], v194 offset:21504
	ds_read_b128 v[224:227], v194 offset:21536
	ds_read_b128 v[228:231], v194 offset:21568
	ds_read_b128 v[232:235], v194 offset:21600
	ds_read_b128 v[126:129], v194 offset:21760
	ds_read_b128 v[130:133], v194 offset:21792
	ds_read_b128 v[134:137], v194 offset:32256
	ds_read_b128 v[212:215], v194 offset:32288
	ds_read_b128 v[154:157], v194 offset:32320
	ds_read_b128 v[158:161], v194 offset:32352
	ds_read_b128 v[204:207], v194 offset:32512
	ds_read_b128 v[186:189], v194 offset:32544
	s_waitcnt lgkmcnt(11)
	v_mfma_f32_32x32x16_bf16 v[48:63], v[220:223], v[64:67], v[236:251]
	s_waitcnt lgkmcnt(10)
	v_mfma_f32_32x32x16_bf16 v[48:63], v[224:227], v[68:71], v[48:63]
	s_waitcnt lgkmcnt(9)
	v_mfma_f32_32x32x16_bf16 v[48:63], v[228:231], v[72:75], v[48:63]
	s_waitcnt lgkmcnt(8)
	v_mfma_f32_32x32x16_bf16 v[48:63], v[232:235], v[76:79], v[48:63]
	s_waitcnt lgkmcnt(7)
	v_mfma_f32_32x32x16_bf16 v[48:63], v[126:129], v[80:83], v[48:63]
	s_waitcnt lgkmcnt(6)
	v_mfma_f32_32x32x16_bf16 v[48:63], v[130:133], v[84:87], v[48:63]
	s_waitcnt lgkmcnt(5)
	v_mfma_f32_32x32x16_bf16 v[32:47], v[134:137], v[64:67], v[236:251]
	s_waitcnt lgkmcnt(4)
	v_mfma_f32_32x32x16_bf16 v[32:47], v[212:215], v[68:71], v[32:47]
	s_waitcnt lgkmcnt(3)
	v_mfma_f32_32x32x16_bf16 v[32:47], v[154:157], v[72:75], v[32:47]
	s_waitcnt lgkmcnt(2)
	v_mfma_f32_32x32x16_bf16 v[32:47], v[158:161], v[76:79], v[32:47]
	s_waitcnt lgkmcnt(1)
	v_mfma_f32_32x32x16_bf16 v[32:47], v[204:207], v[80:83], v[32:47]
	s_waitcnt lgkmcnt(0)
	v_mfma_f32_32x32x16_bf16 v[32:47], v[186:189], v[84:87], v[32:47]
	v_max3_f32 v153, v48, v49, v50
	v_max3_f32 v153, v153, v51, v52
	v_max3_f32 v153, v153, v53, v54
	v_max3_f32 v153, v153, v55, v56
	v_max3_f32 v153, v153, v57, v58
	v_max3_f32 v153, v153, v59, v60
	v_max3_f32 v153, v153, v61, v62
	v_max_f32_e32 v153, v153, v63
	s_nop 3
	v_max3_f32 v153, v153, v32, v33
	v_max3_f32 v153, v153, v34, v35
	v_max3_f32 v153, v153, v36, v37
	v_max3_f32 v153, v153, v38, v39
	v_max3_f32 v153, v153, v40, v41
	v_max3_f32 v153, v153, v42, v43
	v_max3_f32 v153, v153, v44, v45
	v_max3_f32 v153, v153, v46, v47
	v_cmp_lt_f32_e32 vcc, 0x41000000, v153
	s_cbranch_vccz .Lst_norescale_5
	v_mov_b32_e32 v154, v153
	s_nop 1
	v_permlane32_swap_b32_e32 v153, v154
	v_max_f32_e32 v153, v153, v154
	v_max_f32_e32 v154, 0, v153
	v_exp_f32_e64 v152, -v154
	v_sub_f32_e32 v236, v236, v154
	v_sub_f32_e32 v237, v237, v154
	v_sub_f32_e32 v238, v238, v154
	v_sub_f32_e32 v239, v239, v154
	v_sub_f32_e32 v240, v240, v154
	v_sub_f32_e32 v241, v241, v154
	v_sub_f32_e32 v242, v242, v154
	v_sub_f32_e32 v243, v243, v154
	v_sub_f32_e32 v244, v244, v154
	v_sub_f32_e32 v245, v245, v154
	v_sub_f32_e32 v246, v246, v154
	v_sub_f32_e32 v247, v247, v154
	v_sub_f32_e32 v248, v248, v154
	v_sub_f32_e32 v249, v249, v154
	v_sub_f32_e32 v250, v250, v154
	v_sub_f32_e32 v251, v251, v154
	v_pk_mul_f32 v[30:31], v[30:31], v[152:153] op_sel_hi:[1,0]
	v_pk_mul_f32 v[28:29], v[28:29], v[152:153] op_sel_hi:[1,0]
	v_pk_mul_f32 v[26:27], v[26:27], v[152:153] op_sel_hi:[1,0]
	v_pk_mul_f32 v[24:25], v[24:25], v[152:153] op_sel_hi:[1,0]
	v_pk_mul_f32 v[22:23], v[22:23], v[152:153] op_sel_hi:[1,0]
	v_pk_mul_f32 v[20:21], v[20:21], v[152:153] op_sel_hi:[1,0]
	v_pk_mul_f32 v[18:19], v[18:19], v[152:153] op_sel_hi:[1,0]
	v_pk_mul_f32 v[16:17], v[16:17], v[152:153] op_sel_hi:[1,0]
	v_pk_mul_f32 v[14:15], v[14:15], v[152:153] op_sel_hi:[1,0]
	v_pk_mul_f32 v[12:13], v[12:13], v[152:153] op_sel_hi:[1,0]
	v_pk_mul_f32 v[10:11], v[10:11], v[152:153] op_sel_hi:[1,0]
	v_pk_mul_f32 v[8:9], v[8:9], v[152:153] op_sel_hi:[1,0]
	v_pk_mul_f32 v[6:7], v[6:7], v[152:153] op_sel_hi:[1,0]
	v_pk_mul_f32 v[4:5], v[4:5], v[152:153] op_sel_hi:[1,0]
	v_pk_mul_f32 v[2:3], v[2:3], v[152:153] op_sel_hi:[1,0]
	v_pk_mul_f32 v[0:1], v[0:1], v[152:153] op_sel_hi:[1,0]
	v_mul_f32_e32 v151, v151, v152
